# MLA QK block: six K fragments in flight (half-1 uses the idle half-2 fragment registers, body B half-2 the freed softmax temps) with counted lgkmcnt waits; amplified A/B about -3.5 us per attention pa
# speedup vs baseline: 1.0134x; 1.0063x over previous
; __device__ __forceinline__ void finishSM(f32x16& p0, f32x16& p1, float alpha, float& l_reg, bf16x8& pa0, bf16x8& pa1, bf16x8& pa2, bf16x8& pa3) {
; #pragma unroll
;   for (int r = 0; r < 16; ++r) p1[r] = __builtin_amdgcn_exp2f(p1[r]);
;   float ps = 0;
; #pragma unroll
;   for (int r = 0; r < 16; ++r) ps += p0[r];
; #pragma unroll
;   for (int r = 0; r < 16; ++r) ps += p1[r];
;   { auto rr = __builtin_amdgcn_permlane32_swap(__float_as_uint(ps), __float_as_uint(ps), false, false);
;     ps = __uint_as_float(rr[0]) + __uint_as_float(rr[1]); }
;   l_reg = l_reg * alpha + ps;
;     ...
;   PK4(p0, 0, pa0); PK4(p0, 8, pa1); PK4(p1, 0, pa2); PK4(p1, 8, pa3);
;     ...
; }
; template <int DQK> __device__ __forceinline__ void qkt(f32x16& p0, f32x16& p1, const char* Ks, const bf16x8* qr, int r32, int hi) {
;   p0 = f32x16{}; p1 = f32x16{};
; #pragma unroll
;   for (int d0 = 0; d0 < DQK / 16; ++d0) { int cb = (d0 * 16 + hi * 8) * 2;
;     bf16x8 b0 = *reinterpret_cast<const bf16x8*>(Ks + KSWZ(r32, cb));
;     bf16x8 b1 = *reinterpret_cast<const bf16x8*>(Ks + KSWZ(32 + r32, cb));
;     p0 = __builtin_amdgcn_mfma_f32_32x32x16_bf16(b0, qr[d0], p0, 0, 0, 0);
;     p1 = __builtin_amdgcn_mfma_f32_32x32x16_bf16(b1, qr[d0], p1, 0, 0, 0); }
; }
; __device__ __forceinline__ int v_st(int k, int c) { const int kk = (k & ~0xC) | ((k & 4) << 1) | ((k & 8) >> 1); return ((kk >> 3) * 4 + (c >> 5)) * 512 + ((kk & 7) * 32 + (c & 31)) * 2; }
; __device__ __forceinline__ int v_rd_base(int lane) { return ((lane & 3) << 3) | (((lane >> 2) & 3) << 6) | (((lane >> 4) & 1) << 5) | (((lane >> 5) & 1) << 8); }
; template <int OFF> __device__ __forceinline__ s16x4 tr_read(int vb) {
;   s16x4 r; asm volatile("ds_read_b64_tr_b16 %0, %1 offset:%2" : "=&v"(r) : "v"(vb), "i"(OFF) : "memory"); return r;
; }
; template <int D0> __device__ __forceinline__ void pv_one(f32x16& od, int vb, bf16x8 pa0, bf16x8 pa1, bf16x8 pa2, bf16x8 pa3) {
;   const s16x4 l0 = tr_read<v_rd_off(D0, 0, 0)>(vb), h0 = tr_read<v_rd_off(D0, 0, 1)>(vb), l1 = tr_read<v_rd_off(D0, 1, 0)>(vb), h1 = tr_read<v_rd_off(D0, 1, 1)>(vb);
; template <int DQK, int MODE, int ldq, int ldk, int ldv> ...
;     ...
;     SBAR(); qkt<DQK>(pB0, pB1, K_lds + SHM_K, qr, r32, hi);
;     finishSM(pA0, pA1, alA, l_reg, pa0, pa1, pa2, pa3); SBAR();
;     SLOAD(SO, j + 2); SBAR();
;     pv_d0(o, vb0, pa0, pa1, pa2, pa3); BIAS(pB0, pB1, j); partialSM<DQK>(pB0, pB1, m_reg, mnB, alB);
.LBB0_300:
	s_add_i32 s25, s11, -3
	s_cmp_lg_u32 s32, 0
	s_cbranch_scc1 .Lmy_h1B
	ds_read_b128 v[32:35], v148 offset:49152
	ds_read_b128 v[36:39], v148 offset:57344
	ds_read_b128 v[164:167], v152 offset:49152
	ds_read_b128 v[168:171], v152 offset:57344
	ds_read_b128 v[176:179], v151 offset:49152
	ds_read_b128 v[180:183], v151 offset:57344
	s_waitcnt lgkmcnt(5)
	v_mfma_f32_32x32x16_bf16 v[48:63], v[32:35], v[84:87], v[210:225]
	s_waitcnt lgkmcnt(4)
	v_mfma_f32_32x32x16_bf16 v[32:47], v[36:39], v[84:87], v[210:225]
	s_waitcnt lgkmcnt(3)
	v_mfma_f32_32x32x16_bf16 v[48:63], v[164:167], v[80:83], v[48:63]
	s_waitcnt lgkmcnt(2)
	v_mfma_f32_32x32x16_bf16 v[32:47], v[168:171], v[80:83], v[32:47]
	ds_read_b128 v[164:167], v149 offset:49152
	ds_read_b128 v[168:171], v149 offset:57344
	s_waitcnt lgkmcnt(3)
	v_mfma_f32_32x32x16_bf16 v[48:63], v[176:179], v[76:79], v[48:63]
	s_waitcnt lgkmcnt(2)
	v_mfma_f32_32x32x16_bf16 v[32:47], v[180:183], v[76:79], v[32:47]
	ds_read_b128 v[176:179], v150 offset:49152
	ds_read_b128 v[180:183], v150 offset:57344
	s_waitcnt lgkmcnt(3)
	v_mfma_f32_32x32x16_bf16 v[48:63], v[164:167], v[72:75], v[48:63]
	s_waitcnt lgkmcnt(2)
	v_mfma_f32_32x32x16_bf16 v[32:47], v[168:171], v[72:75], v[32:47]
	ds_read_b128 v[164:167], v153 offset:49152
	ds_read_b128 v[168:171], v153 offset:57344
	s_waitcnt lgkmcnt(3)
	v_mfma_f32_32x32x16_bf16 v[48:63], v[176:179], v[68:71], v[48:63]
	s_waitcnt lgkmcnt(2)
	v_mfma_f32_32x32x16_bf16 v[32:47], v[180:183], v[68:71], v[32:47]
	s_waitcnt vmcnt(0)
	ds_write_b128 v146, v[88:91] offset:32768
	ds_write_b128 v147, v[96:99] offset:32768
	ds_write_b128 v145, v[92:95] offset:16384
	s_waitcnt lgkmcnt(4)
	v_mfma_f32_32x32x16_bf16 v[48:63], v[164:167], v[64:67], v[48:63]
	s_waitcnt lgkmcnt(3)
	v_mfma_f32_32x32x16_bf16 v[32:47], v[168:171], v[64:67], v[32:47]
	ds_read_b64_tr_b16 v[184:185], v144 offset:0
	ds_read_b64_tr_b16 v[186:187], v144 offset:0x800
	ds_read_b64_tr_b16 v[188:189], v144 offset:0x1000
	ds_read_b64_tr_b16 v[190:191], v144 offset:0x1800
	ds_read_b64_tr_b16 v[192:193], v144 offset:0x2000
	ds_read_b64_tr_b16 v[194:195], v144 offset:0x2800
	ds_read_b64_tr_b16 v[196:197], v144 offset:0x3000
	ds_read_b64_tr_b16 v[198:199], v144 offset:0x3800
	v_cvt_pk_bf16_f32 v200, v126, v160
	v_cvt_pk_bf16_f32 v201, v127, v161
	v_cvt_pk_bf16_f32 v202, v158, v162
	v_cvt_pk_bf16_f32 v203, v159, v163
	v_cvt_pk_bf16_f32 v226, v118, v121
	v_cvt_pk_bf16_f32 v227, v119, v122
	v_cvt_pk_bf16_f32 v228, v120, v123
	v_cvt_pk_bf16_f32 v229, v124, v125
	v_cvt_pk_bf16_f32 v230, v114, v115
	v_cvt_pk_bf16_f32 v231, v112, v113
	v_cvt_pk_bf16_f32 v232, v108, v109
	v_cvt_pk_bf16_f32 v233, v104, v105
	v_cvt_pk_bf16_f32 v136, v102, v103
	v_cvt_pk_bf16_f32 v137, v110, v111
	v_cvt_pk_bf16_f32 v138, v106, v107
	v_cvt_pk_bf16_f32 v139, v100, v101
	v_add_f32_e32 v155, v126, v160
	v_add_f32_e32 v155, v127, v155
	v_add_f32_e32 v155, v161, v155
	v_add_f32_e32 v155, v158, v155
	v_add_f32_e32 v155, v162, v155
	v_add_f32_e32 v155, v159, v155
	v_add_f32_e32 v155, v163, v155
	v_add_f32_e32 v155, v118, v155
	v_add_f32_e32 v155, v121, v155
	v_add_f32_e32 v155, v119, v155
	v_add_f32_e32 v155, v122, v155
	v_add_f32_e32 v155, v120, v155
	v_add_f32_e32 v155, v123, v155
	v_add_f32_e32 v155, v124, v155
	v_add_f32_e32 v155, v125, v155
	v_add_f32_e32 v155, v114, v155
	v_add_f32_e32 v155, v115, v155
	v_add_f32_e32 v155, v112, v155
	v_add_f32_e32 v155, v113, v155
	v_add_f32_e32 v155, v108, v155
	v_add_f32_e32 v155, v109, v155
	v_add_f32_e32 v155, v104, v155
	v_add_f32_e32 v155, v105, v155
	v_add_f32_e32 v155, v102, v155
	v_add_f32_e32 v155, v103, v155
	v_add_f32_e32 v155, v110, v155
	v_add_f32_e32 v155, v111, v155
	v_add_f32_e32 v155, v106, v155
	v_add_f32_e32 v155, v107, v155
	v_add_f32_e32 v155, v100, v155
	v_add_f32_e32 v155, v101, v155
	s_lshl_b32 s0, s11, 6
	s_cmpk_lt_u32 s25, 0x7e
	s_cselect_b32 s1, s10, s24
	s_add_i32 s1, s1, s0
	s_addk_i32 s1, 0xffc0
	s_mul_i32 s1, s1, 0x300
	s_add_u32 s12, s18, s1
	s_addc_u32 s13, s19, 0
	s_cmpk_lt_u32 s25, 0x7f
	s_cselect_b32 s98, s10, s24
	s_add_i32 s98, s98, s0
	s_addk_i32 s98, 0xff80
	s_lshl_b32 s98, s98, 9
	s_add_u32 s98, s20, s98
	s_addc_u32 s99, s21, 0
	global_load_dwordx4 v[100:103], v134, s[12:13]
	global_load_dwordx4 v[108:111], v135, s[98:99]
	global_load_dwordx4 v[104:107], v238, s[12:13] offset:128
	s_waitcnt lgkmcnt(0)
	s_nop 0
	v_mfma_f32_32x32x16_bf16 v[0:15], v[200:203], v[184:187], v[0:15]
	ds_read_b64_tr_b16 v[184:185], v144 offset:0x200
	ds_read_b64_tr_b16 v[186:187], v144 offset:0xa00
	v_max_f32_e32 v112, v48, v49
	v_max3_f32 v112, v112, v50, v51
	v_max3_f32 v112, v112, v52, v53
	v_max3_f32 v112, v112, v54, v55
	v_max3_f32 v112, v112, v56, v57
	v_mfma_f32_32x32x16_bf16 v[0:15], v[226:229], v[188:191], v[0:15]
	ds_read_b64_tr_b16 v[188:189], v144 offset:0x1200
	ds_read_b64_tr_b16 v[190:191], v144 offset:0x1a00
	v_max3_f32 v112, v112, v58, v59
	v_max3_f32 v112, v112, v60, v61
	v_max3_f32 v112, v112, v62, v63
	v_max3_f32 v112, v112, v32, v33
	v_max3_f32 v112, v112, v34, v35
	v_mfma_f32_32x32x16_bf16 v[0:15], v[230:233], v[192:195], v[0:15]
	ds_read_b64_tr_b16 v[192:193], v144 offset:0x2200
	ds_read_b64_tr_b16 v[194:195], v144 offset:0x2a00
	v_max3_f32 v112, v112, v36, v37
	v_max3_f32 v112, v112, v38, v39
	v_max3_f32 v112, v112, v40, v41
	v_max3_f32 v112, v112, v42, v43
	v_max3_f32 v112, v112, v44, v45
	v_mfma_f32_32x32x16_bf16 v[0:15], v[136:139], v[196:199], v[0:15]
	ds_read_b64_tr_b16 v[196:197], v144 offset:0x3200
	ds_read_b64_tr_b16 v[198:199], v144 offset:0x3a00
	v_max3_f32 v112, v112, v46, v47
	v_cmp_ge_f32_e32 vcc, s80, v112
	s_cmp_eq_u64 vcc, exec
	s_cbranch_scc0 .Lmy_rare_a1
	v_mov_b32_e32 v157, 1.0
	s_mov_b64 vcc, 0

; __device__ __forceinline__ void finishSM(f32x16& p0, f32x16& p1, float alpha, float& l_reg, bf16x8& pa0, bf16x8& pa1, bf16x8& pa2, bf16x8& pa3) {
; #pragma unroll
;   for (int r = 0; r < 16; ++r) p1[r] = __builtin_amdgcn_exp2f(p1[r]);
;   float ps = 0;
; #pragma unroll
;   for (int r = 0; r < 16; ++r) ps += p0[r];
; #pragma unroll
;   for (int r = 0; r < 16; ++r) ps += p1[r];
;   { auto rr = __builtin_amdgcn_permlane32_swap(__float_as_uint(ps), __float_as_uint(ps), false, false);
;     ps = __uint_as_float(rr[0]) + __uint_as_float(rr[1]); }
;   l_reg = l_reg * alpha + ps;
;     ...
;   PK4(p0, 0, pa0); PK4(p0, 8, pa1); PK4(p1, 0, pa2); PK4(p1, 8, pa3);
;     ...
; }
; template <int DQK> __device__ __forceinline__ void qkt(f32x16& p0, f32x16& p1, const char* Ks, const bf16x8* qr, int r32, int hi) {
;   p0 = f32x16{}; p1 = f32x16{};
; #pragma unroll
;   for (int d0 = 0; d0 < DQK / 16; ++d0) { int cb = (d0 * 16 + hi * 8) * 2;
;     bf16x8 b0 = *reinterpret_cast<const bf16x8*>(Ks + KSWZ(r32, cb));
;     bf16x8 b1 = *reinterpret_cast<const bf16x8*>(Ks + KSWZ(32 + r32, cb));
;     p0 = __builtin_amdgcn_mfma_f32_32x32x16_bf16(b0, qr[d0], p0, 0, 0, 0);
;     p1 = __builtin_amdgcn_mfma_f32_32x32x16_bf16(b1, qr[d0], p1, 0, 0, 0); }
; }
; __device__ __forceinline__ int v_st(int k, int c) { const int kk = (k & ~0xC) | ((k & 4) << 1) | ((k & 8) >> 1); return ((kk >> 3) * 4 + (c >> 5)) * 512 + ((kk & 7) * 32 + (c & 31)) * 2; }
; __device__ __forceinline__ int v_rd_base(int lane) { return ((lane & 3) << 3) | (((lane >> 2) & 3) << 6) | (((lane >> 4) & 1) << 5) | (((lane >> 5) & 1) << 8); }
; template <int OFF> __device__ __forceinline__ s16x4 tr_read(int vb) {
;   s16x4 r; asm volatile("ds_read_b64_tr_b16 %0, %1 offset:%2" : "=&v"(r) : "v"(vb), "i"(OFF) : "memory"); return r;
; }
; template <int D0> __device__ __forceinline__ void pv_one(f32x16& od, int vb, bf16x8 pa0, bf16x8 pa1, bf16x8 pa2, bf16x8 pa3) {
;   const s16x4 l0 = tr_read<v_rd_off(D0, 0, 0)>(vb), h0 = tr_read<v_rd_off(D0, 0, 1)>(vb), l1 = tr_read<v_rd_off(D0, 1, 0)>(vb), h1 = tr_read<v_rd_off(D0, 1, 1)>(vb);
; template <int DQK, int MODE, int ldq, int ldk, int ldv> ...
;     ...
;     SBAR(); qkt<DQK>(pB0, pB1, K_lds + SHM_K, qr, r32, hi);
;     finishSM(pA0, pA1, alA, l_reg, pa0, pa1, pa2, pa3); SBAR();
;     SLOAD(SO, j + 2); SBAR();
;     pv_d0(o, vb0, pa0, pa1, pa2, pa3); BIAS(pB0, pB1, j); partialSM<DQK>(pB0, pB1, m_reg, mnB, alB);
.Lmy_h1B:
	s_waitcnt vmcnt(0)
	ds_write_b128 v146, v[88:91] offset:32768
	ds_write_b128 v145, v[92:95] offset:16384
	v_cvt_pk_bf16_f32 v200, v126, v160
	v_cvt_pk_bf16_f32 v201, v127, v161
	v_cvt_pk_bf16_f32 v202, v158, v162
	v_cvt_pk_bf16_f32 v203, v159, v163
	v_cvt_pk_bf16_f32 v226, v118, v121
	v_cvt_pk_bf16_f32 v227, v119, v122
	v_cvt_pk_bf16_f32 v228, v120, v123
	v_cvt_pk_bf16_f32 v229, v124, v125
	v_cvt_pk_bf16_f32 v230, v114, v115
	v_cvt_pk_bf16_f32 v231, v112, v113
	v_cvt_pk_bf16_f32 v232, v108, v109
	v_cvt_pk_bf16_f32 v233, v104, v105
	v_cvt_pk_bf16_f32 v136, v102, v103
	v_cvt_pk_bf16_f32 v137, v110, v111
	v_cvt_pk_bf16_f32 v138, v106, v107
	v_cvt_pk_bf16_f32 v139, v100, v101
	v_add_f32_e32 v155, v126, v160
	v_add_f32_e32 v155, v127, v155
	v_add_f32_e32 v155, v161, v155
	v_add_f32_e32 v155, v158, v155
	v_add_f32_e32 v155, v162, v155
	v_add_f32_e32 v155, v159, v155
	v_add_f32_e32 v155, v163, v155
	v_add_f32_e32 v155, v118, v155
	v_add_f32_e32 v155, v121, v155
	v_add_f32_e32 v155, v119, v155
	v_add_f32_e32 v155, v122, v155
	v_add_f32_e32 v155, v120, v155
	v_add_f32_e32 v155, v123, v155
	v_add_f32_e32 v155, v124, v155
	v_add_f32_e32 v155, v125, v155
	v_add_f32_e32 v155, v114, v155
	v_add_f32_e32 v155, v115, v155
	v_add_f32_e32 v155, v112, v155
	v_add_f32_e32 v155, v113, v155
	v_add_f32_e32 v155, v108, v155
	v_add_f32_e32 v155, v109, v155
	v_add_f32_e32 v155, v104, v155
	v_add_f32_e32 v155, v105, v155
	v_add_f32_e32 v155, v102, v155
	v_add_f32_e32 v155, v103, v155
	v_add_f32_e32 v155, v110, v155
	v_add_f32_e32 v155, v111, v155
	v_add_f32_e32 v155, v106, v155
	v_add_f32_e32 v155, v107, v155
	v_add_f32_e32 v155, v100, v155
	v_add_f32_e32 v155, v101, v155
	s_lshl_b32 s0, s11, 6
	s_cmpk_lt_u32 s25, 0x7e
	s_cselect_b32 s1, s10, s24
	s_add_i32 s1, s1, s0
	s_addk_i32 s1, 0xffc0
	s_mul_i32 s1, s1, 0x300
	s_add_u32 s12, s18, s1
	s_addc_u32 s13, s19, 0
	s_cmpk_lt_u32 s25, 0x7f
	s_cselect_b32 s98, s10, s24
	s_add_i32 s98, s98, s0
	s_addk_i32 s98, 0xff80
	s_lshl_b32 s98, s98, 9
	s_add_u32 s98, s20, s98
	s_addc_u32 s99, s21, 0
	global_load_dwordx4 v[100:103], v134, s[12:13]
	global_load_dwordx4 v[108:111], v135, s[98:99]
	ds_read_b128 v[32:35], v148 offset:49152
	ds_read_b128 v[36:39], v148 offset:57344
	ds_read_b128 v[164:167], v152 offset:49152
	ds_read_b128 v[168:171], v152 offset:57344
	ds_read_b128 v[176:179], v151 offset:49152
	ds_read_b128 v[180:183], v151 offset:57344
	s_waitcnt lgkmcnt(5)
	v_mfma_f32_32x32x16_bf16 v[48:63], v[32:35], v[84:87], v[210:225]
	s_waitcnt lgkmcnt(4)
	v_mfma_f32_32x32x16_bf16 v[32:47], v[36:39], v[84:87], v[210:225]
	s_waitcnt lgkmcnt(3)
	v_mfma_f32_32x32x16_bf16 v[48:63], v[164:167], v[80:83], v[48:63]
	s_waitcnt lgkmcnt(2)
	v_mfma_f32_32x32x16_bf16 v[32:47], v[168:171], v[80:83], v[32:47]
	ds_read_b128 v[164:167], v149 offset:49152
	ds_read_b128 v[168:171], v149 offset:57344
	s_waitcnt lgkmcnt(3)
	v_mfma_f32_32x32x16_bf16 v[48:63], v[176:179], v[76:79], v[48:63]
	s_waitcnt lgkmcnt(2)
	v_mfma_f32_32x32x16_bf16 v[32:47], v[180:183], v[76:79], v[32:47]
	ds_read_b128 v[176:179], v150 offset:49152
	ds_read_b128 v[180:183], v150 offset:57344
	s_waitcnt lgkmcnt(3)
	v_mfma_f32_32x32x16_bf16 v[48:63], v[164:167], v[72:75], v[48:63]
	s_waitcnt lgkmcnt(2)
	v_mfma_f32_32x32x16_bf16 v[32:47], v[168:171], v[72:75], v[32:47]
	ds_read_b128 v[164:167], v153 offset:49152
	ds_read_b128 v[168:171], v153 offset:57344
	s_waitcnt lgkmcnt(3)
	v_mfma_f32_32x32x16_bf16 v[48:63], v[176:179], v[68:71], v[48:63]
	s_waitcnt lgkmcnt(2)
	v_mfma_f32_32x32x16_bf16 v[32:47], v[180:183], v[68:71], v[32:47]
	s_waitcnt lgkmcnt(1)
	v_mfma_f32_32x32x16_bf16 v[48:63], v[164:167], v[64:67], v[48:63]
	s_waitcnt lgkmcnt(0)
	v_mfma_f32_32x32x16_bf16 v[32:47], v[168:171], v[64:67], v[32:47]
	ds_read_b64_tr_b16 v[184:185], v144 offset:0
	ds_read_b64_tr_b16 v[186:187], v144 offset:0x800
	ds_read_b64_tr_b16 v[188:189], v144 offset:0x1000
	ds_read_b64_tr_b16 v[190:191], v144 offset:0x1800
	ds_read_b64_tr_b16 v[192:193], v144 offset:0x2000
	ds_read_b64_tr_b16 v[194:195], v144 offset:0x2800
	ds_read_b64_tr_b16 v[196:197], v144 offset:0x3000
	ds_read_b64_tr_b16 v[198:199], v144 offset:0x3800
	s_waitcnt lgkmcnt(0)
	s_nop 0
	v_mfma_f32_32x32x16_bf16 v[0:15], v[200:203], v[184:187], v[0:15]
	ds_read_b64_tr_b16 v[184:185], v144 offset:0x200
	ds_read_b64_tr_b16 v[186:187], v144 offset:0xa00
	v_mfma_f32_32x32x16_bf16 v[0:15], v[226:229], v[188:191], v[0:15]
	ds_read_b64_tr_b16 v[188:189], v144 offset:0x1200
	ds_read_b64_tr_b16 v[190:191], v144 offset:0x1a00
	v_mfma_f32_32x32x16_bf16 v[0:15], v[230:233], v[192:195], v[0:15]
	ds_read_b64_tr_b16 v[192:193], v144 offset:0x2200
	ds_read_b64_tr_b16 v[194:195], v144 offset:0x2a00
	v_mfma_f32_32x32x16_bf16 v[0:15], v[136:139], v[196:199], v[0:15]
	ds_read_b64_tr_b16 v[196:197], v144 offset:0x3200
	ds_read_b64_tr_b16 v[198:199], v144 offset:0x3a00
	s_waitcnt lgkmcnt(0)
	v_mfma_f32_32x32x16_bf16 v[16:31], v[200:203], v[184:187], v[16:31]
	v_mfma_f32_32x32x16_bf16 v[16:31], v[226:229], v[188:191], v[16:31]
	v_mfma_f32_32x32x16_bf16 v[16:31], v[230:233], v[192:195], v[16:31]
	v_mfma_f32_32x32x16_bf16 v[16:31], v[136:139], v[196:199], v[16:31]
	v_max_f32_e32 v112, v48, v49
	v_max3_f32 v112, v112, v50, v51
	v_max3_f32 v112, v112, v52, v53
	v_max3_f32 v112, v112, v54, v55
	v_max3_f32 v112, v112, v56, v57
	v_max3_f32 v112, v112, v58, v59
	v_max3_f32 v112, v112, v60, v61
	v_max3_f32 v112, v112, v62, v63
	v_max3_f32 v112, v112, v32, v33
	v_max3_f32 v112, v112, v34, v35
	v_max3_f32 v112, v112, v36, v37
	v_max3_f32 v112, v112, v38, v39
	v_max3_f32 v112, v112, v40, v41
	v_max3_f32 v112, v112, v42, v43
	v_max3_f32 v112, v112, v44, v45
	v_max3_f32 v112, v112, v46, v47
	v_cmp_ge_f32_e32 vcc, s80, v112
	s_cmp_eq_u64 vcc, exec
	s_cbranch_scc0 .Lmy_rare_b1
	v_mov_b32_e32 v157, 1.0
	s_mov_b64 vcc, 0

; #define SBAR() __builtin_amdgcn_sched_barrier(0)
; template <int DQK> __device__ __forceinline__ void qkt(f32x16& p0, f32x16& p1, const char* Ks, const bf16x8* qr, int r32, int hi) {
;   p0 = f32x16{}; p1 = f32x16{};
; #pragma unroll
;   for (int d0 = 0; d0 < DQK / 16; ++d0) { int cb = (d0 * 16 + hi * 8) * 2;
;     bf16x8 b0 = *reinterpret_cast<const bf16x8*>(Ks + KSWZ(r32, cb));
;     bf16x8 b1 = *reinterpret_cast<const bf16x8*>(Ks + KSWZ(32 + r32, cb));
;     p0 = __builtin_amdgcn_mfma_f32_32x32x16_bf16(b0, qr[d0], p0, 0, 0, 0);
;     p1 = __builtin_amdgcn_mfma_f32_32x32x16_bf16(b1, qr[d0], p1, 0, 0, 0); }
; }
; __device__ __forceinline__ int v_st(int k, int c) { const int kk = (k & ~0xC) | ((k & 4) << 1) | ((k & 8) >> 1); return ((kk >> 3) * 4 + (c >> 5)) * 512 + ((kk & 7) * 32 + (c & 31)) * 2; }
; __device__ __forceinline__ int v_rd_base(int lane) { return ((lane & 3) << 3) | (((lane >> 2) & 3) << 6) | (((lane >> 4) & 1) << 5) | (((lane >> 5) & 1) << 8); }
; template <int OFF> __device__ __forceinline__ s16x4 tr_read(int vb) {
;   s16x4 r; asm volatile("ds_read_b64_tr_b16 %0, %1 offset:%2" : "=&v"(r) : "v"(vb), "i"(OFF) : "memory"); return r;
; }
; template <int D0> __device__ __forceinline__ void pv_one(f32x16& od, int vb, bf16x8 pa0, bf16x8 pa1, bf16x8 pa2, bf16x8 pa3) {
;   const s16x4 l0 = tr_read<v_rd_off(D0, 0, 0)>(vb), h0 = tr_read<v_rd_off(D0, 0, 1)>(vb), l1 = tr_read<v_rd_off(D0, 1, 0)>(vb), h1 = tr_read<v_rd_off(D0, 1, 1)>(vb);
;   const s16x4 l2 = tr_read<v_rd_off(D0, 2, 0)>(vb), h2 = tr_read<v_rd_off(D0, 2, 1)>(vb), l3 = tr_read<v_rd_off(D0, 3, 0)>(vb), h3 = tr_read<v_rd_off(D0, 3, 1)>(vb);
;   asm volatile("s_waitcnt lgkmcnt(0)" ::: "memory"); SBAR();
;   od = __builtin_amdgcn_mfma_f32_32x32x16_bf16(pa0, PKLH(l0, h0), od, 0, 0, 0);
;   od = __builtin_amdgcn_mfma_f32_32x32x16_bf16(pa1, PKLH(l1, h1), od, 0, 0, 0);
;   od = __builtin_amdgcn_mfma_f32_32x32x16_bf16(pa2, PKLH(l2, h2), od, 0, 0, 0);
;   od = __builtin_amdgcn_mfma_f32_32x32x16_bf16(pa3, PKLH(l3, h3), od, 0, 0, 0);
; }
; template <int DQK, int MODE, int ldq, int ldk, int ldv> ...
;     ...
;     SBAR(); qkt<DQK>(pA0, pA1, K_lds, qr, r32, hi);
;     finishSM(pB0, pB1, alB, l_reg, pa0, pa1, pa2, pa3); SBAR();
;     if (j + 3 < NT) SLOAD(SE, j + 3); SBAR();
;     pv_d0(o, vb0 + (int)SHM_V, pa0, pa1, pa2, pa3); BIAS(pA0, pA1, j + 1); partialSM<DQK>(pA0, pA1, m_reg, mnA, alA);
.Lmy_h2B_306:
	ds_read_b128 v[32:35], v148 offset:32768
	ds_read_b128 v[36:39], v148 offset:40960
	ds_read_b128 v[176:179], v152 offset:32768
	ds_read_b128 v[180:183], v152 offset:40960
	ds_read_b128 v[164:167], v151 offset:32768
	ds_read_b128 v[168:171], v151 offset:40960
	s_waitcnt lgkmcnt(5)
	v_mfma_f32_32x32x16_bf16 v[48:63], v[32:35], v[84:87], v[210:225]
	s_waitcnt lgkmcnt(4)
	v_mfma_f32_32x32x16_bf16 v[32:47], v[36:39], v[84:87], v[210:225]
	s_waitcnt lgkmcnt(3)
	v_mfma_f32_32x32x16_bf16 v[48:63], v[176:179], v[80:83], v[48:63]
	s_waitcnt lgkmcnt(2)
	v_mfma_f32_32x32x16_bf16 v[32:47], v[180:183], v[80:83], v[32:47]
	ds_read_b128 v[176:179], v149 offset:32768
	ds_read_b128 v[180:183], v149 offset:40960
	s_waitcnt lgkmcnt(3)
	v_mfma_f32_32x32x16_bf16 v[48:63], v[164:167], v[76:79], v[48:63]
	s_waitcnt lgkmcnt(2)
	v_mfma_f32_32x32x16_bf16 v[32:47], v[168:171], v[76:79], v[32:47]
	ds_read_b128 v[164:167], v150 offset:32768
	ds_read_b128 v[168:171], v150 offset:40960
	s_waitcnt lgkmcnt(3)
	v_mfma_f32_32x32x16_bf16 v[48:63], v[176:179], v[72:75], v[48:63]
	s_waitcnt lgkmcnt(2)
	v_mfma_f32_32x32x16_bf16 v[32:47], v[180:183], v[72:75], v[32:47]
	ds_read_b128 v[176:179], v153 offset:32768
	ds_read_b128 v[180:183], v153 offset:40960
	s_waitcnt lgkmcnt(3)
	v_mfma_f32_32x32x16_bf16 v[48:63], v[164:167], v[68:71], v[48:63]
	s_waitcnt lgkmcnt(2)
	v_mfma_f32_32x32x16_bf16 v[32:47], v[168:171], v[68:71], v[32:47]
	s_waitcnt lgkmcnt(1)
	v_mfma_f32_32x32x16_bf16 v[48:63], v[176:179], v[64:67], v[48:63]
	s_waitcnt lgkmcnt(0)
	v_mfma_f32_32x32x16_bf16 v[32:47], v[180:183], v[64:67], v[32:47]
	ds_read_b64_tr_b16 v[184:185], v143 offset:0
	ds_read_b64_tr_b16 v[186:187], v143 offset:0x800
	ds_read_b64_tr_b16 v[188:189], v143 offset:0x1000
	ds_read_b64_tr_b16 v[190:191], v143 offset:0x1800
	ds_read_b64_tr_b16 v[192:193], v143 offset:0x2000
	ds_read_b64_tr_b16 v[194:195], v143 offset:0x2800
	ds_read_b64_tr_b16 v[196:197], v143 offset:0x3000
	ds_read_b64_tr_b16 v[198:199], v143 offset:0x3800
	s_waitcnt lgkmcnt(0)
	s_nop 0
	v_mfma_f32_32x32x16_bf16 v[0:15], v[200:203], v[184:187], v[0:15]
	ds_read_b64_tr_b16 v[184:185], v143 offset:0x200
	ds_read_b64_tr_b16 v[186:187], v143 offset:0xa00
	v_mfma_f32_32x32x16_bf16 v[0:15], v[226:229], v[188:191], v[0:15]
	ds_read_b64_tr_b16 v[188:189], v143 offset:0x1200
	ds_read_b64_tr_b16 v[190:191], v143 offset:0x1a00
	v_mfma_f32_32x32x16_bf16 v[0:15], v[230:233], v[192:195], v[0:15]
	ds_read_b64_tr_b16 v[192:193], v143 offset:0x2200
	ds_read_b64_tr_b16 v[194:195], v143 offset:0x2a00
	v_mfma_f32_32x32x16_bf16 v[0:15], v[136:139], v[196:199], v[0:15]
	ds_read_b64_tr_b16 v[196:197], v143 offset:0x3200
	ds_read_b64_tr_b16 v[198:199], v143 offset:0x3a00
	s_waitcnt lgkmcnt(0)
	v_mfma_f32_32x32x16_bf16 v[16:31], v[200:203], v[184:187], v[16:31]
	v_mfma_f32_32x32x16_bf16 v[16:31], v[226:229], v[188:191], v[16:31]
	v_mfma_f32_32x32x16_bf16 v[16:31], v[230:233], v[192:195], v[16:31]
	v_mfma_f32_32x32x16_bf16 v[16:31], v[136:139], v[196:199], v[16:31]
	v_max_f32_e32 v112, v48, v49
	v_max3_f32 v112, v112, v50, v51
	v_max3_f32 v112, v112, v52, v53
	v_max3_f32 v112, v112, v54, v55
	v_max3_f32 v112, v112, v56, v57
	v_max3_f32 v112, v112, v58, v59
	v_max3_f32 v112, v112, v60, v61
	v_max3_f32 v112, v112, v62, v63
	v_max3_f32 v112, v112, v32, v33
	v_max3_f32 v112, v112, v34, v35
	v_max3_f32 v112, v112, v36, v37
	v_max3_f32 v112, v112, v38, v39
	v_max3_f32 v112, v112, v40, v41
	v_max3_f32 v112, v112, v42, v43
	v_max3_f32 v112, v112, v44, v45
	v_max3_f32 v112, v112, v46, v47
	v_cmp_ge_f32_e32 vcc, s80, v112
	s_cmp_eq_u64 vcc, exec
	s_cbranch_scc0 .Lmy_rare_b2
	v_mov_b32_e32 v117, 1.0
	s_mov_b64 vcc, 0
